# v_li + M1 epilogue full-line stores (DPP row_ror:8 lane exchange, 8 rows x 128B per store)
# speedup vs baseline: 1.0045x; 1.0045x over previous
.LBB0_958:
	v_and_b32_e32 v180, 8, v0
	v_sub_u32_e32 v146, v146, v180
	v_sub_u32_e32 v142, v142, v180
	v_sub_u32_e32 v158, v158, v180
	v_lshl_add_u32 v181, v180, 2, v226
	v_pk_mul_f32 v[126:127], v[126:127], v[140:141] op_sel_hi:[1,0]
	v_lshl_or_b32 v2, s59, 8, v181
	v_pk_mul_f32 v[130:131], v[130:131], v[140:141] op_sel_hi:[1,0]
	v_pk_mul_f32 v[128:129], v[128:129], v[140:141] op_sel_hi:[1,0]
	v_max_f32_e32 v126, 0, v126
	v_ashrrev_i32_e32 v3, 31, v2
	v_lshlrev_b64 v[138:139], 13, v[146:147]
	v_pk_mul_f32 v[132:133], v[132:133], v[140:141] op_sel_hi:[1,0]
	v_mul_f32_e32 v141, v126, v126
	v_max_f32_e32 v126, 0, v131
	v_max_f32_e32 v127, 0, v127
	v_max_f32_e32 v128, 0, v128
	v_lshl_add_u64 v[138:139], s[4:5], 0, v[138:139]
	v_lshlrev_b64 v[2:3], 1, v[2:3]
	v_max_f32_e32 v130, 0, v130
	v_mul_f32_e32 v126, v126, v126
	v_mul_f32_e32 v131, v127, v127
	v_max_f32_e32 v127, 0, v132
	v_mul_f32_e32 v132, v128, v128
	v_max_f32_e32 v128, 0, v133
	v_max_f32_e32 v129, 0, v129
	v_pk_mul_f32 v[118:119], v[118:119], v[140:141] op_sel_hi:[1,0]
	v_lshl_add_u64 v[138:139], v[138:139], 0, v[2:3]
	v_mul_f32_e32 v130, v130, v130
	v_mul_f32_e32 v127, v127, v127
	v_mul_f32_e32 v128, v128, v128
	v_mul_f32_e32 v129, v129, v129
	v_cvt_pk_bf16_f32 v126, v130, v126
	v_pk_mul_f32 v[122:123], v[122:123], v[140:141] op_sel_hi:[1,0]
	v_pk_mul_f32 v[120:121], v[120:121], v[140:141] op_sel_hi:[1,0]
	v_max_f32_e32 v118, 0, v118
	v_cvt_pk_bf16_f32 v127, v127, v128
	v_cvt_pk_bf16_f32 v128, v141, v131
	v_cvt_pk_bf16_f32 v129, v132, v129
	v_pk_mul_f32 v[124:125], v[124:125], v[140:141] op_sel_hi:[1,0]
	v_max_f32_e32 v119, 0, v119
	v_mul_f32_e32 v184, v118, v118
	v_max_f32_e32 v118, 0, v123
	v_max_f32_e32 v120, 0, v120
	v_max_f32_e32 v122, 0, v122
	v_mul_f32_e32 v118, v118, v118
	v_mul_f32_e32 v123, v119, v119
	v_max_f32_e32 v119, 0, v124
	v_mul_f32_e32 v124, v120, v120
	v_max_f32_e32 v120, 0, v125
	v_max_f32_e32 v121, 0, v121
	v_mul_f32_e32 v122, v122, v122
	v_mul_f32_e32 v119, v119, v119
	v_mul_f32_e32 v120, v120, v120
	v_mul_f32_e32 v121, v121, v121
	v_cvt_pk_bf16_f32 v118, v122, v118
	v_cvt_pk_bf16_f32 v119, v119, v120
	v_cvt_pk_bf16_f32 v120, v184, v123
	v_cvt_pk_bf16_f32 v121, v124, v121
	v_mov_b32_e32 v176, v126
	v_mov_b32_e32 v177, v127
	v_mov_b32_e32 v178, v128
	v_mov_b32_e32 v179, v129
	v_mov_b32_dpp v126, v118 row_ror:8 row_mask:0xf bank_mask:0xc
	v_mov_b32_dpp v127, v119 row_ror:8 row_mask:0xf bank_mask:0xc
	v_mov_b32_dpp v128, v120 row_ror:8 row_mask:0xf bank_mask:0xc
	v_mov_b32_dpp v129, v121 row_ror:8 row_mask:0xf bank_mask:0xc
	v_mov_b32_dpp v118, v176 row_ror:8 row_mask:0xf bank_mask:0x3
	v_mov_b32_dpp v119, v177 row_ror:8 row_mask:0xf bank_mask:0x3
	v_mov_b32_dpp v120, v178 row_ror:8 row_mask:0xf bank_mask:0x3
	v_mov_b32_dpp v121, v179 row_ror:8 row_mask:0xf bank_mask:0x3
	global_store_dwordx4 v[138:139], v[126:129], off sc1
	v_add_co_u32_e32 v182, vcc, 0x10000, v138
	v_addc_co_u32_e32 v183, vcc, 0, v139, vcc
	global_store_dwordx4 v[182:183], v[118:121], off sc1
	v_pk_mul_f32 v[110:111], v[110:111], v[144:145] op_sel_hi:[1,0]
	v_pk_mul_f32 v[114:115], v[114:115], v[144:145] op_sel_hi:[1,0]
	v_or_b32_e32 v118, 16, v146
	v_ashrrev_i32_e32 v119, 31, v118
	v_pk_mul_f32 v[112:113], v[112:113], v[144:145] op_sel_hi:[1,0]
	v_max_f32_e32 v110, 0, v110
	v_lshlrev_b64 v[118:119], 13, v[118:119]
	v_pk_mul_f32 v[116:117], v[116:117], v[144:145] op_sel_hi:[1,0]
	v_mul_f32_e32 v120, v110, v110
	v_max_f32_e32 v110, 0, v115
	v_max_f32_e32 v111, 0, v111
	v_max_f32_e32 v112, 0, v112
	v_lshl_add_u64 v[118:119], s[4:5], 0, v[118:119]
	v_max_f32_e32 v114, 0, v114
	v_mul_f32_e32 v110, v110, v110
	v_mul_f32_e32 v115, v111, v111
	v_max_f32_e32 v111, 0, v116
	v_mul_f32_e32 v116, v112, v112
	v_max_f32_e32 v112, 0, v117
	v_max_f32_e32 v113, 0, v113
	v_pk_mul_f32 v[102:103], v[102:103], v[144:145] op_sel_hi:[1,0]
	v_lshl_add_u64 v[118:119], v[118:119], 0, v[2:3]
	v_mul_f32_e32 v114, v114, v114
	v_mul_f32_e32 v111, v111, v111
	v_mul_f32_e32 v112, v112, v112
	v_mul_f32_e32 v113, v113, v113
	v_cvt_pk_bf16_f32 v110, v114, v110
	v_pk_mul_f32 v[106:107], v[106:107], v[144:145] op_sel_hi:[1,0]
	v_pk_mul_f32 v[104:105], v[104:105], v[144:145] op_sel_hi:[1,0]
	v_max_f32_e32 v102, 0, v102
	v_cvt_pk_bf16_f32 v111, v111, v112
	v_cvt_pk_bf16_f32 v112, v120, v115
	v_cvt_pk_bf16_f32 v113, v116, v113
	v_pk_mul_f32 v[108:109], v[108:109], v[144:145] op_sel_hi:[1,0]
	v_max_f32_e32 v103, 0, v103
	v_mul_f32_e32 v184, v102, v102
	v_max_f32_e32 v102, 0, v107
	v_max_f32_e32 v104, 0, v104
	v_max_f32_e32 v106, 0, v106
	v_mul_f32_e32 v102, v102, v102
	v_mul_f32_e32 v107, v103, v103
	v_max_f32_e32 v103, 0, v108
	v_mul_f32_e32 v108, v104, v104
	v_max_f32_e32 v104, 0, v109
	v_max_f32_e32 v105, 0, v105
	v_mul_f32_e32 v106, v106, v106
	v_mul_f32_e32 v103, v103, v103
	v_mul_f32_e32 v104, v104, v104
	v_mul_f32_e32 v105, v105, v105
	v_cvt_pk_bf16_f32 v102, v106, v102
	v_cvt_pk_bf16_f32 v103, v103, v104
	v_cvt_pk_bf16_f32 v104, v184, v107
	v_cvt_pk_bf16_f32 v105, v108, v105
	v_mov_b32_e32 v176, v110
	v_mov_b32_e32 v177, v111
	v_mov_b32_e32 v178, v112
	v_mov_b32_e32 v179, v113
	v_mov_b32_dpp v110, v102 row_ror:8 row_mask:0xf bank_mask:0xc
	v_mov_b32_dpp v111, v103 row_ror:8 row_mask:0xf bank_mask:0xc
	v_mov_b32_dpp v112, v104 row_ror:8 row_mask:0xf bank_mask:0xc
	v_mov_b32_dpp v113, v105 row_ror:8 row_mask:0xf bank_mask:0xc
	v_mov_b32_dpp v102, v176 row_ror:8 row_mask:0xf bank_mask:0x3
	v_mov_b32_dpp v103, v177 row_ror:8 row_mask:0xf bank_mask:0x3
	v_mov_b32_dpp v104, v178 row_ror:8 row_mask:0xf bank_mask:0x3
	v_mov_b32_dpp v105, v179 row_ror:8 row_mask:0xf bank_mask:0x3
	global_store_dwordx4 v[118:119], v[110:113], off sc1
	v_add_co_u32_e32 v182, vcc, 0x10000, v118
	v_addc_co_u32_e32 v183, vcc, 0, v119, vcc
	global_store_dwordx4 v[182:183], v[102:105], off sc1
	v_pk_mul_f32 v[94:95], v[94:95], v[148:149] op_sel_hi:[1,0]
	v_pk_mul_f32 v[98:99], v[98:99], v[148:149] op_sel_hi:[1,0]
	v_or_b32_e32 v102, 32, v146
	v_ashrrev_i32_e32 v103, 31, v102
	v_pk_mul_f32 v[96:97], v[96:97], v[148:149] op_sel_hi:[1,0]
	v_max_f32_e32 v94, 0, v94
	v_lshlrev_b64 v[102:103], 13, v[102:103]
	v_pk_mul_f32 v[100:101], v[100:101], v[148:149] op_sel_hi:[1,0]
	v_mul_f32_e32 v104, v94, v94
	v_max_f32_e32 v94, 0, v99
	v_max_f32_e32 v95, 0, v95
	v_max_f32_e32 v96, 0, v96
	v_lshl_add_u64 v[102:103], s[4:5], 0, v[102:103]
	v_max_f32_e32 v98, 0, v98
	v_mul_f32_e32 v94, v94, v94
	v_mul_f32_e32 v99, v95, v95
	v_max_f32_e32 v95, 0, v100
	v_mul_f32_e32 v100, v96, v96
	v_max_f32_e32 v96, 0, v101
	v_max_f32_e32 v97, 0, v97
	v_pk_mul_f32 v[86:87], v[86:87], v[148:149] op_sel_hi:[1,0]
	v_lshl_add_u64 v[102:103], v[102:103], 0, v[2:3]
	v_mul_f32_e32 v98, v98, v98
	v_mul_f32_e32 v95, v95, v95
	v_mul_f32_e32 v96, v96, v96
	v_mul_f32_e32 v97, v97, v97
	v_cvt_pk_bf16_f32 v94, v98, v94
	v_pk_mul_f32 v[90:91], v[90:91], v[148:149] op_sel_hi:[1,0]
	v_pk_mul_f32 v[88:89], v[88:89], v[148:149] op_sel_hi:[1,0]
	v_max_f32_e32 v86, 0, v86
	v_cvt_pk_bf16_f32 v95, v95, v96
	v_cvt_pk_bf16_f32 v96, v104, v99
	v_cvt_pk_bf16_f32 v97, v100, v97
	v_pk_mul_f32 v[92:93], v[92:93], v[148:149] op_sel_hi:[1,0]
	v_max_f32_e32 v87, 0, v87
	v_mul_f32_e32 v184, v86, v86
	v_max_f32_e32 v86, 0, v91
	v_max_f32_e32 v88, 0, v88
	v_max_f32_e32 v90, 0, v90
	v_mul_f32_e32 v86, v86, v86
	v_mul_f32_e32 v91, v87, v87
	v_max_f32_e32 v87, 0, v92
	v_mul_f32_e32 v92, v88, v88
	v_max_f32_e32 v88, 0, v93
	v_max_f32_e32 v89, 0, v89
	v_mul_f32_e32 v90, v90, v90
	v_mul_f32_e32 v87, v87, v87
	v_mul_f32_e32 v88, v88, v88
	v_mul_f32_e32 v89, v89, v89
	v_cvt_pk_bf16_f32 v86, v90, v86
	v_cvt_pk_bf16_f32 v87, v87, v88
	v_cvt_pk_bf16_f32 v88, v184, v91
	v_cvt_pk_bf16_f32 v89, v92, v89
	v_mov_b32_e32 v176, v94
	v_mov_b32_e32 v177, v95
	v_mov_b32_e32 v178, v96
	v_mov_b32_e32 v179, v97
	v_mov_b32_dpp v94, v86 row_ror:8 row_mask:0xf bank_mask:0xc
	v_mov_b32_dpp v95, v87 row_ror:8 row_mask:0xf bank_mask:0xc
	v_mov_b32_dpp v96, v88 row_ror:8 row_mask:0xf bank_mask:0xc
	v_mov_b32_dpp v97, v89 row_ror:8 row_mask:0xf bank_mask:0xc
	v_mov_b32_dpp v86, v176 row_ror:8 row_mask:0xf bank_mask:0x3
	v_mov_b32_dpp v87, v177 row_ror:8 row_mask:0xf bank_mask:0x3
	v_mov_b32_dpp v88, v178 row_ror:8 row_mask:0xf bank_mask:0x3
	v_mov_b32_dpp v89, v179 row_ror:8 row_mask:0xf bank_mask:0x3
	global_store_dwordx4 v[102:103], v[94:97], off sc1
	v_add_co_u32_e32 v182, vcc, 0x10000, v102
	v_addc_co_u32_e32 v183, vcc, 0, v103, vcc
	global_store_dwordx4 v[182:183], v[86:89], off sc1
	v_pk_mul_f32 v[78:79], v[78:79], v[150:151] op_sel_hi:[1,0]
	v_pk_mul_f32 v[82:83], v[82:83], v[150:151] op_sel_hi:[1,0]
	v_or_b32_e32 v86, 48, v146
	v_ashrrev_i32_e32 v87, 31, v86
	v_pk_mul_f32 v[80:81], v[80:81], v[150:151] op_sel_hi:[1,0]
	v_max_f32_e32 v78, 0, v78
	v_lshlrev_b64 v[86:87], 13, v[86:87]
	v_pk_mul_f32 v[84:85], v[84:85], v[150:151] op_sel_hi:[1,0]
	v_mul_f32_e32 v88, v78, v78
	v_max_f32_e32 v78, 0, v83
	v_max_f32_e32 v79, 0, v79
	v_max_f32_e32 v80, 0, v80
	v_lshl_add_u64 v[86:87], s[4:5], 0, v[86:87]
	v_max_f32_e32 v82, 0, v82
	v_mul_f32_e32 v78, v78, v78
	v_mul_f32_e32 v83, v79, v79
	v_max_f32_e32 v79, 0, v84
	v_mul_f32_e32 v84, v80, v80
	v_max_f32_e32 v80, 0, v85
	v_max_f32_e32 v81, 0, v81
	v_pk_mul_f32 v[72:73], v[72:73], v[150:151] op_sel_hi:[1,0]
	v_pk_mul_f32 v[70:71], v[70:71], v[150:151] op_sel_hi:[1,0]
	v_lshl_add_u64 v[86:87], v[86:87], 0, v[2:3]
	v_mul_f32_e32 v82, v82, v82
	v_mul_f32_e32 v79, v79, v79
	v_mul_f32_e32 v80, v80, v80
	v_mul_f32_e32 v81, v81, v81
	v_cvt_pk_bf16_f32 v78, v82, v78
	v_pk_mul_f32 v[76:77], v[76:77], v[150:151] op_sel_hi:[1,0]
	v_pk_mul_f32 v[74:75], v[74:75], v[150:151] op_sel_hi:[1,0]
	v_max_f32_e32 v70, 0, v70
	v_max_f32_e32 v71, 0, v71
	v_max_f32_e32 v72, 0, v72
	v_cvt_pk_bf16_f32 v79, v79, v80
	v_cvt_pk_bf16_f32 v80, v88, v83
	v_cvt_pk_bf16_f32 v81, v84, v81
	v_max_f32_e32 v74, 0, v74
	v_max_f32_e32 v73, 0, v73
	v_mul_f32_e32 v184, v70, v70
	v_max_f32_e32 v70, 0, v75
	v_mul_f32_e32 v75, v71, v71
	v_max_f32_e32 v71, 0, v76
	v_mul_f32_e32 v76, v72, v72
	v_max_f32_e32 v72, 0, v77
	v_mul_f32_e32 v70, v70, v70
	v_mul_f32_e32 v71, v71, v71
	v_mul_f32_e32 v72, v72, v72
	v_pk_mul_f32 v[62:63], v[62:63], v[136:137] op_sel_hi:[1,0]
	v_mul_f32_e32 v74, v74, v74
	v_mul_f32_e32 v73, v73, v73
	v_cvt_pk_bf16_f32 v70, v74, v70
	v_cvt_pk_bf16_f32 v71, v71, v72
	v_cvt_pk_bf16_f32 v72, v184, v75
	v_pk_mul_f32 v[66:67], v[66:67], v[136:137] op_sel_hi:[1,0]
	v_pk_mul_f32 v[64:65], v[64:65], v[136:137] op_sel_hi:[1,0]
	v_max_f32_e32 v62, 0, v62
	v_cvt_pk_bf16_f32 v73, v76, v73
	v_mov_b32_e32 v176, v78
	v_mov_b32_e32 v177, v79
	v_mov_b32_e32 v178, v80
	v_mov_b32_e32 v179, v81
	v_mov_b32_dpp v78, v70 row_ror:8 row_mask:0xf bank_mask:0xc
	v_mov_b32_dpp v79, v71 row_ror:8 row_mask:0xf bank_mask:0xc
	v_mov_b32_dpp v80, v72 row_ror:8 row_mask:0xf bank_mask:0xc
	v_mov_b32_dpp v81, v73 row_ror:8 row_mask:0xf bank_mask:0xc
	v_mov_b32_dpp v70, v176 row_ror:8 row_mask:0xf bank_mask:0x3
	v_mov_b32_dpp v71, v177 row_ror:8 row_mask:0xf bank_mask:0x3
	v_mov_b32_dpp v72, v178 row_ror:8 row_mask:0xf bank_mask:0x3
	v_mov_b32_dpp v73, v179 row_ror:8 row_mask:0xf bank_mask:0x3
	global_store_dwordx4 v[86:87], v[78:81], off sc1
	v_add_co_u32_e32 v182, vcc, 0x10000, v86
	v_addc_co_u32_e32 v183, vcc, 0, v87, vcc
	global_store_dwordx4 v[182:183], v[70:73], off sc1
	v_pk_mul_f32 v[68:69], v[68:69], v[136:137] op_sel_hi:[1,0]
	v_max_f32_e32 v63, 0, v63
	v_lshlrev_b64 v[70:71], 13, v[158:159]
	v_mul_f32_e32 v72, v62, v62
	v_max_f32_e32 v62, 0, v67
	v_max_f32_e32 v64, 0, v64
	v_lshl_add_u64 v[70:71], s[4:5], 0, v[70:71]
	v_max_f32_e32 v66, 0, v66
	v_mul_f32_e32 v62, v62, v62
	v_mul_f32_e32 v67, v63, v63
	v_max_f32_e32 v63, 0, v68
	v_mul_f32_e32 v68, v64, v64
	v_max_f32_e32 v64, 0, v69
	v_max_f32_e32 v65, 0, v65
	v_pk_mul_f32 v[54:55], v[54:55], v[136:137] op_sel_hi:[1,0]
	v_lshl_add_u64 v[70:71], v[70:71], 0, v[2:3]
	v_mul_f32_e32 v66, v66, v66
	v_mul_f32_e32 v63, v63, v63
	v_mul_f32_e32 v64, v64, v64
	v_mul_f32_e32 v65, v65, v65
	v_cvt_pk_bf16_f32 v62, v66, v62
	v_pk_mul_f32 v[60:61], v[60:61], v[136:137] op_sel_hi:[1,0]
	v_pk_mul_f32 v[58:59], v[58:59], v[136:137] op_sel_hi:[1,0]
	v_pk_mul_f32 v[56:57], v[56:57], v[136:137] op_sel_hi:[1,0]
	v_max_f32_e32 v54, 0, v54
	v_max_f32_e32 v55, 0, v55
	v_cvt_pk_bf16_f32 v63, v63, v64
	v_cvt_pk_bf16_f32 v64, v72, v67
	v_cvt_pk_bf16_f32 v65, v68, v65
	v_max_f32_e32 v56, 0, v56
	v_max_f32_e32 v58, 0, v58
	v_mul_f32_e32 v184, v54, v54
	v_max_f32_e32 v54, 0, v59
	v_mul_f32_e32 v59, v55, v55
	v_max_f32_e32 v55, 0, v60
	v_mul_f32_e32 v54, v54, v54
	v_mul_f32_e32 v55, v55, v55
	v_mul_f32_e32 v60, v56, v56
	v_max_f32_e32 v56, 0, v61
	v_max_f32_e32 v57, 0, v57
	v_mul_f32_e32 v58, v58, v58
	v_mul_f32_e32 v56, v56, v56
	v_mul_f32_e32 v57, v57, v57
	v_cvt_pk_bf16_f32 v54, v58, v54
	v_cvt_pk_bf16_f32 v55, v55, v56
	v_ashrrev_i32_e32 v143, 31, v142
	v_pk_mul_f32 v[46:47], v[46:47], v[136:137] op_sel:[0,1]
	v_cvt_pk_bf16_f32 v56, v184, v59
	v_cvt_pk_bf16_f32 v57, v60, v57
	v_mov_b32_e32 v176, v62
	v_mov_b32_e32 v177, v63
	v_mov_b32_e32 v178, v64
	v_mov_b32_e32 v179, v65
	v_mov_b32_dpp v62, v54 row_ror:8 row_mask:0xf bank_mask:0xc
	v_mov_b32_dpp v63, v55 row_ror:8 row_mask:0xf bank_mask:0xc
	v_mov_b32_dpp v64, v56 row_ror:8 row_mask:0xf bank_mask:0xc
	v_mov_b32_dpp v65, v57 row_ror:8 row_mask:0xf bank_mask:0xc
	v_mov_b32_dpp v54, v176 row_ror:8 row_mask:0xf bank_mask:0x3
	v_mov_b32_dpp v55, v177 row_ror:8 row_mask:0xf bank_mask:0x3
	v_mov_b32_dpp v56, v178 row_ror:8 row_mask:0xf bank_mask:0x3
	v_mov_b32_dpp v57, v179 row_ror:8 row_mask:0xf bank_mask:0x3
	global_store_dwordx4 v[70:71], v[62:65], off sc1
	v_add_co_u32_e32 v182, vcc, 0x10000, v70
	v_addc_co_u32_e32 v183, vcc, 0, v71, vcc
	global_store_dwordx4 v[182:183], v[54:57], off sc1
	v_pk_mul_f32 v[50:51], v[50:51], v[136:137] op_sel:[0,1]
	v_pk_mul_f32 v[48:49], v[48:49], v[136:137] op_sel:[0,1]
	v_lshlrev_b64 v[54:55], 13, v[142:143]
	v_max_f32_e32 v46, 0, v46
	v_lshl_add_u64 v[54:55], s[4:5], 0, v[54:55]
	v_pk_mul_f32 v[52:53], v[52:53], v[136:137] op_sel:[0,1]
	v_max_f32_e32 v50, 0, v50
	v_mul_f32_e32 v56, v46, v46
	v_max_f32_e32 v46, 0, v51
	v_max_f32_e32 v47, 0, v47
	v_max_f32_e32 v48, 0, v48
	v_lshl_add_u64 v[2:3], v[54:55], 0, v[2:3]
	v_mul_f32_e32 v50, v50, v50
	v_mul_f32_e32 v46, v46, v46
	v_mul_f32_e32 v51, v47, v47
	v_max_f32_e32 v47, 0, v52
	v_mul_f32_e32 v52, v48, v48
	v_max_f32_e32 v48, 0, v53
	s_mov_b32 s13, 0x20000
	v_mul_f32_e32 v47, v47, v47
	v_max_f32_e32 v49, 0, v49
	v_mul_f32_e32 v48, v48, v48
	v_cvt_pk_bf16_f32 v46, v50, v46
	v_add_co_u32_e32 v50, vcc, s13, v2
	v_pk_mul_f32 v[40:41], v[40:41], v[136:137] op_sel:[0,1]
	v_pk_mul_f32 v[38:39], v[38:39], v[136:137] op_sel:[0,1]
	v_mul_f32_e32 v49, v49, v49
	v_cvt_pk_bf16_f32 v47, v47, v48
	v_cvt_pk_bf16_f32 v48, v56, v51
	v_addc_co_u32_e32 v51, vcc, 0, v3, vcc
	v_pk_mul_f32 v[44:45], v[44:45], v[136:137] op_sel:[0,1]
	v_pk_mul_f32 v[42:43], v[42:43], v[136:137] op_sel:[0,1]
	v_max_f32_e32 v38, 0, v38
	v_max_f32_e32 v39, 0, v39
	v_max_f32_e32 v40, 0, v40
	v_cvt_pk_bf16_f32 v49, v52, v49
	s_mov_b64 s[22:23], 0x20000
	v_max_f32_e32 v41, 0, v41
	v_mul_f32_e32 v184, v38, v38
	v_max_f32_e32 v38, 0, v43
	v_mul_f32_e32 v43, v39, v39
	v_max_f32_e32 v39, 0, v44
	v_mul_f32_e32 v44, v40, v40
	v_max_f32_e32 v40, 0, v45
	v_mul_f32_e32 v39, v39, v39
	v_mul_f32_e32 v40, v40, v40
	v_pk_mul_f32 v[30:31], v[30:31], v[152:153] op_sel_hi:[1,0]
	v_lshl_add_u64 v[54:55], v[2:3], 0, s[22:23]
	v_max_f32_e32 v42, 0, v42
	v_mul_f32_e32 v38, v38, v38
	v_mul_f32_e32 v41, v41, v41
	v_cvt_pk_bf16_f32 v39, v39, v40
	v_cvt_pk_bf16_f32 v40, v184, v43
	v_pk_mul_f32 v[34:35], v[34:35], v[152:153] op_sel_hi:[1,0]
	v_pk_mul_f32 v[32:33], v[32:33], v[152:153] op_sel_hi:[1,0]
	v_max_f32_e32 v30, 0, v30
	v_mul_f32_e32 v42, v42, v42
	v_cvt_pk_bf16_f32 v38, v42, v38
	v_cvt_pk_bf16_f32 v41, v44, v41
	v_mov_b32_e32 v176, v46
	v_mov_b32_e32 v177, v47
	v_mov_b32_e32 v178, v48
	v_mov_b32_e32 v179, v49
	v_mov_b32_dpp v46, v38 row_ror:8 row_mask:0xf bank_mask:0xc
	v_mov_b32_dpp v47, v39 row_ror:8 row_mask:0xf bank_mask:0xc
	v_mov_b32_dpp v48, v40 row_ror:8 row_mask:0xf bank_mask:0xc
	v_mov_b32_dpp v49, v41 row_ror:8 row_mask:0xf bank_mask:0xc
	v_mov_b32_dpp v38, v176 row_ror:8 row_mask:0xf bank_mask:0x3
	v_mov_b32_dpp v39, v177 row_ror:8 row_mask:0xf bank_mask:0x3
	v_mov_b32_dpp v40, v178 row_ror:8 row_mask:0xf bank_mask:0x3
	v_mov_b32_dpp v41, v179 row_ror:8 row_mask:0xf bank_mask:0x3
	global_store_dwordx4 v[50:51], v[46:49], off sc1
	v_add_co_u32_e32 v182, vcc, 0x10000, v50
	v_addc_co_u32_e32 v183, vcc, 0, v51, vcc
	global_store_dwordx4 v[182:183], v[38:41], off sc1
	v_pk_mul_f32 v[36:37], v[36:37], v[152:153] op_sel_hi:[1,0]
	v_max_f32_e32 v34, 0, v34
	v_mul_f32_e32 v40, v30, v30
	v_max_f32_e32 v30, 0, v35
	v_max_f32_e32 v31, 0, v31
	v_max_f32_e32 v32, 0, v32
	v_mul_f32_e32 v34, v34, v34
	v_mul_f32_e32 v30, v30, v30
	v_mul_f32_e32 v35, v31, v31
	v_max_f32_e32 v31, 0, v36
	v_mul_f32_e32 v36, v32, v32
	v_max_f32_e32 v32, 0, v37
	v_mul_f32_e32 v31, v31, v31
	v_max_f32_e32 v33, 0, v33
	v_mul_f32_e32 v32, v32, v32
	v_cvt_pk_bf16_f32 v30, v34, v30
	v_add_co_u32_e32 v34, vcc, s72, v2
	v_pk_mul_f32 v[24:25], v[24:25], v[152:153] op_sel_hi:[1,0]
	v_pk_mul_f32 v[22:23], v[22:23], v[152:153] op_sel_hi:[1,0]
	v_mul_f32_e32 v33, v33, v33
	v_cvt_pk_bf16_f32 v31, v31, v32
	v_cvt_pk_bf16_f32 v32, v40, v35
	v_addc_co_u32_e32 v35, vcc, 0, v3, vcc
	v_pk_mul_f32 v[28:29], v[28:29], v[152:153] op_sel_hi:[1,0]
	v_pk_mul_f32 v[26:27], v[26:27], v[152:153] op_sel_hi:[1,0]
	v_max_f32_e32 v22, 0, v22
	v_max_f32_e32 v23, 0, v23
	v_max_f32_e32 v24, 0, v24
	v_cvt_pk_bf16_f32 v33, v36, v33
	s_mov_b64 s[22:23], 0x40000
	v_max_f32_e32 v26, 0, v26
	v_mul_f32_e32 v184, v22, v22
	v_max_f32_e32 v22, 0, v27
	v_mul_f32_e32 v27, v23, v23
	v_max_f32_e32 v23, 0, v28
	v_mul_f32_e32 v28, v24, v24
	v_max_f32_e32 v24, 0, v29
	v_mul_f32_e32 v22, v22, v22
	v_mul_f32_e32 v23, v23, v23
	v_max_f32_e32 v25, 0, v25
	v_mul_f32_e32 v24, v24, v24
	v_pk_mul_f32 v[16:17], v[16:17], v[154:155] op_sel_hi:[1,0]
	v_pk_mul_f32 v[14:15], v[14:15], v[154:155] op_sel_hi:[1,0]
	v_lshl_add_u64 v[38:39], v[2:3], 0, s[22:23]
	v_mul_f32_e32 v26, v26, v26
	v_mul_f32_e32 v25, v25, v25
	v_cvt_pk_bf16_f32 v22, v26, v22
	v_cvt_pk_bf16_f32 v23, v23, v24
	v_cvt_pk_bf16_f32 v24, v184, v27
	s_mov_b64 s[22:23], 0x60000
	v_pk_mul_f32 v[20:21], v[20:21], v[154:155] op_sel_hi:[1,0]
	v_pk_mul_f32 v[18:19], v[18:19], v[154:155] op_sel_hi:[1,0]
	v_max_f32_e32 v14, 0, v14
	v_max_f32_e32 v15, 0, v15
	v_max_f32_e32 v16, 0, v16
	s_mov_b32 s13, 0x60000
	v_cvt_pk_bf16_f32 v25, v28, v25
	v_mov_b32_e32 v176, v30
	v_mov_b32_e32 v177, v31
	v_mov_b32_e32 v178, v32
	v_mov_b32_e32 v179, v33
	v_mov_b32_dpp v30, v22 row_ror:8 row_mask:0xf bank_mask:0xc
	v_mov_b32_dpp v31, v23 row_ror:8 row_mask:0xf bank_mask:0xc
	v_mov_b32_dpp v32, v24 row_ror:8 row_mask:0xf bank_mask:0xc
	v_mov_b32_dpp v33, v25 row_ror:8 row_mask:0xf bank_mask:0xc
	v_mov_b32_dpp v22, v176 row_ror:8 row_mask:0xf bank_mask:0x3
	v_mov_b32_dpp v23, v177 row_ror:8 row_mask:0xf bank_mask:0x3
	v_mov_b32_dpp v24, v178 row_ror:8 row_mask:0xf bank_mask:0x3
	v_mov_b32_dpp v25, v179 row_ror:8 row_mask:0xf bank_mask:0x3
	global_store_dwordx4 v[34:35], v[30:33], off sc1
	v_add_co_u32_e32 v182, vcc, 0x10000, v34
	v_addc_co_u32_e32 v183, vcc, 0, v35, vcc
	global_store_dwordx4 v[182:183], v[22:25], off sc1
	v_max_f32_e32 v17, 0, v17
	v_pk_mul_f32 v[6:7], v[6:7], v[154:155] op_sel_hi:[1,0]
	v_lshl_add_u64 v[22:23], v[2:3], 0, s[22:23]
	v_mul_f32_e32 v24, v14, v14
	v_max_f32_e32 v14, 0, v19
	v_mul_f32_e32 v19, v15, v15
	v_max_f32_e32 v15, 0, v20
	v_mul_f32_e32 v20, v16, v16
	v_max_f32_e32 v16, 0, v21
	v_add_co_u32_e32 v2, vcc, s13, v2
	v_max_f32_e32 v18, 0, v18
	v_mul_f32_e32 v14, v14, v14
	v_mul_f32_e32 v15, v15, v15
	v_mul_f32_e32 v16, v16, v16
	v_mul_f32_e32 v17, v17, v17
	v_addc_co_u32_e32 v3, vcc, 0, v3, vcc
	v_pk_mul_f32 v[10:11], v[10:11], v[154:155] op_sel_hi:[1,0]
	v_pk_mul_f32 v[8:9], v[8:9], v[154:155] op_sel_hi:[1,0]
	v_max_f32_e32 v6, 0, v6
	v_max_f32_e32 v7, 0, v7
	v_mul_f32_e32 v18, v18, v18
	v_cvt_pk_bf16_f32 v14, v18, v14
	v_cvt_pk_bf16_f32 v15, v15, v16
	v_cvt_pk_bf16_f32 v16, v24, v19
	v_cvt_pk_bf16_f32 v17, v20, v17
	v_mov_b64_e32 v[188:189], v[2:3]
	v_pk_mul_f32 v[2:3], v[12:13], v[154:155] op_sel_hi:[1,0]
	v_mul_f32_e32 v12, v6, v6
	v_max_f32_e32 v6, 0, v11
	v_mul_f32_e32 v11, v7, v7
	v_max_f32_e32 v7, 0, v8
	v_mul_f32_e32 v13, v7, v7
	v_max_f32_e32 v7, 0, v9
	v_max_f32_e32 v10, 0, v10
	v_mul_f32_e32 v6, v6, v6
	v_max_f32_e32 v2, 0, v2
	v_max_f32_e32 v3, 0, v3
	v_mul_f32_e32 v9, v7, v7
	v_mul_f32_e32 v10, v10, v10
	v_mul_f32_e32 v2, v2, v2
	v_mul_f32_e32 v3, v3, v3
	v_cvt_pk_bf16_f32 v6, v10, v6
	v_cvt_pk_bf16_f32 v7, v2, v3
	v_cvt_pk_bf16_f32 v8, v12, v11
	v_cvt_pk_bf16_f32 v9, v13, v9
	v_mov_b32_e32 v176, v14
	v_mov_b32_e32 v177, v15
	v_mov_b32_e32 v178, v16
	v_mov_b32_e32 v179, v17
	v_mov_b32_dpp v14, v6 row_ror:8 row_mask:0xf bank_mask:0xc
	v_mov_b32_dpp v15, v7 row_ror:8 row_mask:0xf bank_mask:0xc
	v_mov_b32_dpp v16, v8 row_ror:8 row_mask:0xf bank_mask:0xc
	v_mov_b32_dpp v17, v9 row_ror:8 row_mask:0xf bank_mask:0xc
	v_mov_b32_dpp v6, v176 row_ror:8 row_mask:0xf bank_mask:0x3
	v_mov_b32_dpp v7, v177 row_ror:8 row_mask:0xf bank_mask:0x3
	v_mov_b32_dpp v8, v178 row_ror:8 row_mask:0xf bank_mask:0x3
	v_mov_b32_dpp v9, v179 row_ror:8 row_mask:0xf bank_mask:0x3
	global_store_dwordx4 v[188:189], v[14:17], off sc1
	v_add_co_u32_e32 v182, vcc, 0x10000, v188
	v_addc_co_u32_e32 v183, vcc, 0, v189, vcc
	global_store_dwordx4 v[182:183], v[6:9], off sc1
	s_andn2_b64 vcc, exec, s[20:21]
	s_mov_b64 s[20:21], -1
	s_cbranch_vccnz .LBB0_936
	s_andn2_b64 vcc, exec, s[2:3]
	s_cbranch_vccnz .LBB0_935
	s_barrier
	s_branch .LBB0_935
